# v45 plus the same all-loads-first rewrite for the w_ukv and w_uq weight transposes in P0
# speedup vs baseline: 1.0182x; 1.0045x over previous
.LBB0_67:
	s_andn2_b64 vcc, exec, s[4:5]
	s_cbranch_vccnz .LBB0_87
	s_add_i32 s4, s68, 0xcac0
	s_and_b32 s5, s4, 0xffff
	s_mul_i32 s16, s5, 0xaaab
	s_lshr_b32 s18, s16, 16
	s_lshr_b32 s16, s16, 22
	s_mulk_i32 s16, 0x60
	s_sub_i32 s4, s4, s16
	s_lshl_b32 s4, s4, 5
	s_and_b32 s56, s4, 0xffe0
	s_and_b32 s16, s18, 0xffc0
	v_or_b32_e32 v5, s56, v25
	v_lshlrev_b32_e32 v50, 2, v5
	v_or_b32_e32 v5, s16, v62
	v_mov_b32_e32 v51, v7
	v_mul_u32_u24_e32 v6, 0x3000, v5
	v_or_b32_e32 v5, s16, v63
	v_lshl_add_u64 v[34:35], v[50:51], 0, v[6:7]
	v_mul_u32_u24_e32 v6, 0x3000, v5
	v_or_b32_e32 v5, s16, v64
	v_lshl_add_u64 v[38:39], v[50:51], 0, v[6:7]
	v_mul_u32_u24_e32 v6, 0x3000, v5
	v_or_b32_e32 v5, s16, v65
	v_lshl_add_u64 v[40:41], v[50:51], 0, v[6:7]
	v_mul_u32_u24_e32 v6, 0x3000, v5
	v_or_b32_e32 v5, s16, v66
	v_lshl_add_u64 v[42:43], v[50:51], 0, v[6:7]
	v_mul_u32_u24_e32 v6, 0x3000, v5
	v_or_b32_e32 v5, s16, v67
	v_lshl_add_u64 v[44:45], v[50:51], 0, v[6:7]
	v_mul_u32_u24_e32 v6, 0x3000, v5
	v_or_b32_e32 v5, s16, v68
	s_mul_hi_u32 s4, s5, 0x2aaaaab
	v_lshl_add_u64 v[46:47], v[50:51], 0, v[6:7]
	v_mul_u32_u24_e32 v6, 0x3000, v5
	v_or_b32_e32 v5, s16, v2
	v_lshl_or_b32 v36, s4, 8, v32
	v_lshl_add_u64 v[48:49], v[50:51], 0, v[6:7]
	v_mad_u64_u32 v[50:51], s[4:5], v5, s64, v[50:51]
	v_lshl_add_u64 v[34:35], s[20:21], 0, v[34:35]
	v_mov_b32_e32 v37, v3
	v_lshl_add_u64 v[38:39], s[20:21], 0, v[38:39]
	v_lshl_add_u64 v[40:41], s[20:21], 0, v[40:41]
	v_lshl_add_u64 v[42:43], s[20:21], 0, v[42:43]
	v_lshl_add_u64 v[44:45], s[20:21], 0, v[44:45]
	v_lshl_add_u64 v[46:47], s[20:21], 0, v[46:47]
	v_lshl_add_u64 v[48:49], s[20:21], 0, v[48:49]
	v_lshlrev_b32_e32 v6, 2, v5
	v_lshl_add_u64 v[50:51], s[20:21], 0, v[50:51]
	s_mov_b64 s[18:19], 0
	s_mov_b64 s[58:59], s[30:31]
	v_mov_b32_e32 v5, v61
	s_and_b64 vcc, exec, s[34:35]
	s_cbranch_vccz .LBB0_70
	global_load_dword v100, v[50:51], off
	global_load_dword v101, v[48:49], off
	global_load_dword v102, v[46:47], off
	global_load_dword v103, v[44:45], off
	global_load_dword v104, v[42:43], off
	global_load_dword v105, v[40:41], off
	global_load_dword v106, v[38:39], off
	global_load_dword v107, v[34:35], off
	v_lshl_add_u64 v[166:167], s[58:59], 0, v[6:7]
	global_load_dword v132, v[166:167], off
	v_lshl_add_u64 v[166:167], s[58:59], 0, v[36:37]
	global_load_dword v133, v[166:167], off offset:8
	v_lshl_add_u64 v[166:167], s[58:59], 0, v[36:37]
	global_load_dword v134, v[166:167], off offset:16
	v_lshl_add_u64 v[166:167], s[58:59], 0, v[36:37]
	global_load_dword v135, v[166:167], off offset:24
	v_lshl_add_u64 v[166:167], s[58:59], 0, v[36:37]
	global_load_dword v136, v[166:167], off offset:32
	v_lshl_add_u64 v[166:167], s[58:59], 0, v[36:37]
	global_load_dword v137, v[166:167], off offset:40
	v_lshl_add_u64 v[166:167], s[58:59], 0, v[36:37]
	global_load_dword v138, v[166:167], off offset:48
	v_lshl_add_u64 v[166:167], s[58:59], 0, v[36:37]
	global_load_dword v139, v[166:167], off offset:56
	s_mov_b32 s18, 0x30000
	s_mov_b32 s19, 0
	v_lshl_add_u64 v[164:165], v[50:51], 0, s[18:19]
	global_load_dword v108, v[164:165], off
	v_lshl_add_u64 v[164:165], v[48:49], 0, s[18:19]
	global_load_dword v109, v[164:165], off
	v_lshl_add_u64 v[164:165], v[46:47], 0, s[18:19]
	global_load_dword v110, v[164:165], off
	v_lshl_add_u64 v[164:165], v[44:45], 0, s[18:19]
	global_load_dword v111, v[164:165], off
	v_lshl_add_u64 v[164:165], v[42:43], 0, s[18:19]
	global_load_dword v112, v[164:165], off
	v_lshl_add_u64 v[164:165], v[40:41], 0, s[18:19]
	global_load_dword v113, v[164:165], off
	v_lshl_add_u64 v[164:165], v[38:39], 0, s[18:19]
	global_load_dword v114, v[164:165], off
	v_lshl_add_u64 v[164:165], v[34:35], 0, s[18:19]
	global_load_dword v115, v[164:165], off
	v_lshl_add_u64 v[166:167], s[58:59], 0, v[6:7]
	global_load_dword v140, v[166:167], off offset:64
	v_lshl_add_u64 v[166:167], s[58:59], 0, v[36:37]
	global_load_dword v141, v[166:167], off offset:72
	v_lshl_add_u64 v[166:167], s[58:59], 0, v[36:37]
	global_load_dword v142, v[166:167], off offset:80
	v_lshl_add_u64 v[166:167], s[58:59], 0, v[36:37]
	global_load_dword v143, v[166:167], off offset:88
	v_lshl_add_u64 v[166:167], s[58:59], 0, v[36:37]
	global_load_dword v144, v[166:167], off offset:96
	v_lshl_add_u64 v[166:167], s[58:59], 0, v[36:37]
	global_load_dword v145, v[166:167], off offset:104
	v_lshl_add_u64 v[166:167], s[58:59], 0, v[36:37]
	global_load_dword v146, v[166:167], off offset:112
	v_lshl_add_u64 v[166:167], s[58:59], 0, v[36:37]
	global_load_dword v147, v[166:167], off offset:120
	s_waitcnt vmcnt(16)
	v_mul_f32_e32 v100, v100, v132
	v_mul_f32_e32 v101, v101, v133
	v_mul_f32_e32 v102, v102, v134
	v_mul_f32_e32 v103, v103, v135
	v_mul_f32_e32 v104, v104, v136
	v_mul_f32_e32 v105, v105, v137
	v_mul_f32_e32 v106, v106, v138
	v_mul_f32_e32 v107, v107, v139
	ds_write_b32 v5, v100
	ds_write_b32 v5, v101 offset:264
	ds_write_b32 v5, v102 offset:528
	ds_write_b32 v5, v103 offset:792
	ds_write_b32 v5, v104 offset:1056
	ds_write_b32 v5, v105 offset:1320
	ds_write_b32 v5, v106 offset:1584
	ds_write_b32 v5, v107 offset:1848
	s_waitcnt vmcnt(0)
	v_mul_f32_e32 v108, v108, v140
	v_mul_f32_e32 v109, v109, v141
	v_mul_f32_e32 v110, v110, v142
	v_mul_f32_e32 v111, v111, v143
	v_mul_f32_e32 v112, v112, v144
	v_mul_f32_e32 v113, v113, v145
	v_mul_f32_e32 v114, v114, v146
	v_mul_f32_e32 v115, v115, v147
	ds_write_b32 v5, v108 offset:2112
	ds_write_b32 v5, v109 offset:2376
	ds_write_b32 v5, v110 offset:2640
	ds_write_b32 v5, v111 offset:2904
	ds_write_b32 v5, v112 offset:3168
	ds_write_b32 v5, v113 offset:3432
	ds_write_b32 v5, v114 offset:3696
	ds_write_b32 v5, v115 offset:3960
	s_mov_b32 s18, 0x60000
	s_mov_b32 s19, 0
	v_lshl_add_u64 v[164:165], v[50:51], 0, s[18:19]
	global_load_dword v100, v[164:165], off
	v_lshl_add_u64 v[164:165], v[48:49], 0, s[18:19]
	global_load_dword v101, v[164:165], off
	v_lshl_add_u64 v[164:165], v[46:47], 0, s[18:19]
	global_load_dword v102, v[164:165], off
	v_lshl_add_u64 v[164:165], v[44:45], 0, s[18:19]
	global_load_dword v103, v[164:165], off
	v_lshl_add_u64 v[164:165], v[42:43], 0, s[18:19]
	global_load_dword v104, v[164:165], off
	v_lshl_add_u64 v[164:165], v[40:41], 0, s[18:19]
	global_load_dword v105, v[164:165], off
	v_lshl_add_u64 v[164:165], v[38:39], 0, s[18:19]
	global_load_dword v106, v[164:165], off
	v_lshl_add_u64 v[164:165], v[34:35], 0, s[18:19]
	global_load_dword v107, v[164:165], off
	v_lshl_add_u64 v[166:167], s[58:59], 0, v[6:7]
	global_load_dword v132, v[166:167], off offset:128
	v_lshl_add_u64 v[166:167], s[58:59], 0, v[36:37]
	global_load_dword v133, v[166:167], off offset:136
	v_lshl_add_u64 v[166:167], s[58:59], 0, v[36:37]
	global_load_dword v134, v[166:167], off offset:144
	v_lshl_add_u64 v[166:167], s[58:59], 0, v[36:37]
	global_load_dword v135, v[166:167], off offset:152
	v_lshl_add_u64 v[166:167], s[58:59], 0, v[36:37]
	global_load_dword v136, v[166:167], off offset:160
	v_lshl_add_u64 v[166:167], s[58:59], 0, v[36:37]
	global_load_dword v137, v[166:167], off offset:168
	v_lshl_add_u64 v[166:167], s[58:59], 0, v[36:37]
	global_load_dword v138, v[166:167], off offset:176
	v_lshl_add_u64 v[166:167], s[58:59], 0, v[36:37]
	global_load_dword v139, v[166:167], off offset:184
	s_mov_b32 s18, 0x90000
	s_mov_b32 s19, 0
	v_lshl_add_u64 v[164:165], v[50:51], 0, s[18:19]
	global_load_dword v108, v[164:165], off
	v_lshl_add_u64 v[164:165], v[48:49], 0, s[18:19]
	global_load_dword v109, v[164:165], off
	v_lshl_add_u64 v[164:165], v[46:47], 0, s[18:19]
	global_load_dword v110, v[164:165], off
	v_lshl_add_u64 v[164:165], v[44:45], 0, s[18:19]
	global_load_dword v111, v[164:165], off
	v_lshl_add_u64 v[164:165], v[42:43], 0, s[18:19]
	global_load_dword v112, v[164:165], off
	v_lshl_add_u64 v[164:165], v[40:41], 0, s[18:19]
	global_load_dword v113, v[164:165], off
	v_lshl_add_u64 v[164:165], v[38:39], 0, s[18:19]
	global_load_dword v114, v[164:165], off
	v_lshl_add_u64 v[164:165], v[34:35], 0, s[18:19]
	global_load_dword v115, v[164:165], off
	v_lshl_add_u64 v[166:167], s[58:59], 0, v[6:7]
	global_load_dword v140, v[166:167], off offset:192
	v_lshl_add_u64 v[166:167], s[58:59], 0, v[36:37]
	global_load_dword v141, v[166:167], off offset:200
	v_lshl_add_u64 v[166:167], s[58:59], 0, v[36:37]
	global_load_dword v142, v[166:167], off offset:208
	v_lshl_add_u64 v[166:167], s[58:59], 0, v[36:37]
	global_load_dword v143, v[166:167], off offset:216
	v_lshl_add_u64 v[166:167], s[58:59], 0, v[36:37]
	global_load_dword v144, v[166:167], off offset:224
	v_lshl_add_u64 v[166:167], s[58:59], 0, v[36:37]
	global_load_dword v145, v[166:167], off offset:232
	v_lshl_add_u64 v[166:167], s[58:59], 0, v[36:37]
	global_load_dword v146, v[166:167], off offset:240
	v_lshl_add_u64 v[166:167], s[58:59], 0, v[36:37]
	global_load_dword v147, v[166:167], off offset:248
	s_waitcnt vmcnt(16)
	v_mul_f32_e32 v100, v100, v132
	v_mul_f32_e32 v101, v101, v133
	v_mul_f32_e32 v102, v102, v134
	v_mul_f32_e32 v103, v103, v135
	v_mul_f32_e32 v104, v104, v136
	v_mul_f32_e32 v105, v105, v137
	v_mul_f32_e32 v106, v106, v138
	v_mul_f32_e32 v107, v107, v139
	ds_write_b32 v5, v100 offset:4224
	ds_write_b32 v5, v101 offset:4488
	ds_write_b32 v5, v102 offset:4752
	ds_write_b32 v5, v103 offset:5016
	ds_write_b32 v5, v104 offset:5280
	ds_write_b32 v5, v105 offset:5544
	ds_write_b32 v5, v106 offset:5808
	ds_write_b32 v5, v107 offset:6072
	s_waitcnt vmcnt(0)
	v_mul_f32_e32 v108, v108, v140
	v_mul_f32_e32 v109, v109, v141
	v_mul_f32_e32 v110, v110, v142
	v_mul_f32_e32 v111, v111, v143
	v_mul_f32_e32 v112, v112, v144
	v_mul_f32_e32 v113, v113, v145
	v_mul_f32_e32 v114, v114, v146
	v_mul_f32_e32 v115, v115, v147
	ds_write_b32 v5, v108 offset:6336
	ds_write_b32 v5, v109 offset:6600
	ds_write_b32 v5, v110 offset:6864
	ds_write_b32 v5, v111 offset:7128
	ds_write_b32 v5, v112 offset:7392
	ds_write_b32 v5, v113 offset:7656
	ds_write_b32 v5, v114 offset:7920
	ds_write_b32 v5, v115 offset:8184
	v_add_u32_e32 v5, 0x2100, v5
	s_mov_b32 s18, 0xc0000
	s_mov_b32 s19, 0
	s_add_u32 s58, s58, 0x100
	s_addc_u32 s59, s59, 0
	s_branch .LBB0_86

.LBB0_93:
	s_lshl_b32 s4, s16, 6
	s_and_b32 s16, s4, 0xffc0
	v_or_b32_e32 v5, s16, v62
	v_lshlrev_b64 v[50:51], 2, v[6:7]
	v_mul_u32_u24_e32 v6, 0x2400, v5
	v_or_b32_e32 v5, s16, v63
	v_lshl_add_u64 v[34:35], v[50:51], 0, v[6:7]
	v_mul_u32_u24_e32 v6, 0x2400, v5
	v_or_b32_e32 v5, s16, v64
	v_lshl_add_u64 v[38:39], v[50:51], 0, v[6:7]
	v_mul_u32_u24_e32 v6, 0x2400, v5
	v_or_b32_e32 v5, s16, v65
	v_lshl_add_u64 v[40:41], v[50:51], 0, v[6:7]
	v_mul_u32_u24_e32 v6, 0x2400, v5
	v_or_b32_e32 v5, s16, v66
	v_lshl_add_u64 v[42:43], v[50:51], 0, v[6:7]
	v_mul_u32_u24_e32 v6, 0x2400, v5
	v_or_b32_e32 v5, s16, v67
	v_lshl_add_u64 v[44:45], v[50:51], 0, v[6:7]
	v_mul_u32_u24_e32 v6, 0x2400, v5
	v_or_b32_e32 v5, s16, v68
	s_mul_hi_u32 s4, s18, 0x38e38e4
	v_lshl_add_u64 v[46:47], v[50:51], 0, v[6:7]
	v_mul_u32_u24_e32 v6, 0x2400, v5
	v_or_b32_e32 v5, s16, v2
	v_lshl_or_b32 v36, s4, 8, v32
	v_lshl_add_u64 v[48:49], v[50:51], 0, v[6:7]
	v_mad_u64_u32 v[50:51], s[4:5], v5, s65, v[50:51]
	v_lshl_add_u64 v[34:35], s[28:29], 0, v[34:35]
	v_mov_b32_e32 v37, v3
	v_lshl_add_u64 v[38:39], s[28:29], 0, v[38:39]
	v_lshl_add_u64 v[40:41], s[28:29], 0, v[40:41]
	v_lshl_add_u64 v[42:43], s[28:29], 0, v[42:43]
	v_lshl_add_u64 v[44:45], s[28:29], 0, v[44:45]
	v_lshl_add_u64 v[46:47], s[28:29], 0, v[46:47]
	v_lshl_add_u64 v[48:49], s[28:29], 0, v[48:49]
	v_lshlrev_b32_e32 v6, 2, v5
	v_lshl_add_u64 v[50:51], s[28:29], 0, v[50:51]
	s_mov_b64 s[18:19], 0
	s_mov_b64 s[58:59], s[26:27]
	v_mov_b32_e32 v5, v61
	s_and_b64 vcc, exec, s[54:55]
	s_cbranch_vccz .LBB0_95
	global_load_dword v100, v[50:51], off
	global_load_dword v101, v[48:49], off
	global_load_dword v102, v[46:47], off
	global_load_dword v103, v[44:45], off
	global_load_dword v104, v[42:43], off
	global_load_dword v105, v[40:41], off
	global_load_dword v106, v[38:39], off
	global_load_dword v107, v[34:35], off
	v_lshl_add_u64 v[166:167], s[58:59], 0, v[6:7]
	global_load_dword v132, v[166:167], off
	v_lshl_add_u64 v[166:167], s[58:59], 0, v[36:37]
	global_load_dword v133, v[166:167], off offset:8
	v_lshl_add_u64 v[166:167], s[58:59], 0, v[36:37]
	global_load_dword v134, v[166:167], off offset:16
	v_lshl_add_u64 v[166:167], s[58:59], 0, v[36:37]
	global_load_dword v135, v[166:167], off offset:24
	v_lshl_add_u64 v[166:167], s[58:59], 0, v[36:37]
	global_load_dword v136, v[166:167], off offset:32
	v_lshl_add_u64 v[166:167], s[58:59], 0, v[36:37]
	global_load_dword v137, v[166:167], off offset:40
	v_lshl_add_u64 v[166:167], s[58:59], 0, v[36:37]
	global_load_dword v138, v[166:167], off offset:48
	v_lshl_add_u64 v[166:167], s[58:59], 0, v[36:37]
	global_load_dword v139, v[166:167], off offset:56
	s_mov_b32 s18, 0x24000
	s_mov_b32 s19, 0
	v_lshl_add_u64 v[164:165], v[50:51], 0, s[18:19]
	global_load_dword v108, v[164:165], off
	v_lshl_add_u64 v[164:165], v[48:49], 0, s[18:19]
	global_load_dword v109, v[164:165], off
	v_lshl_add_u64 v[164:165], v[46:47], 0, s[18:19]
	global_load_dword v110, v[164:165], off
	v_lshl_add_u64 v[164:165], v[44:45], 0, s[18:19]
	global_load_dword v111, v[164:165], off
	v_lshl_add_u64 v[164:165], v[42:43], 0, s[18:19]
	global_load_dword v112, v[164:165], off
	v_lshl_add_u64 v[164:165], v[40:41], 0, s[18:19]
	global_load_dword v113, v[164:165], off
	v_lshl_add_u64 v[164:165], v[38:39], 0, s[18:19]
	global_load_dword v114, v[164:165], off
	v_lshl_add_u64 v[164:165], v[34:35], 0, s[18:19]
	global_load_dword v115, v[164:165], off
	v_lshl_add_u64 v[166:167], s[58:59], 0, v[6:7]
	global_load_dword v140, v[166:167], off offset:64
	v_lshl_add_u64 v[166:167], s[58:59], 0, v[36:37]
	global_load_dword v141, v[166:167], off offset:72
	v_lshl_add_u64 v[166:167], s[58:59], 0, v[36:37]
	global_load_dword v142, v[166:167], off offset:80
	v_lshl_add_u64 v[166:167], s[58:59], 0, v[36:37]
	global_load_dword v143, v[166:167], off offset:88
	v_lshl_add_u64 v[166:167], s[58:59], 0, v[36:37]
	global_load_dword v144, v[166:167], off offset:96
	v_lshl_add_u64 v[166:167], s[58:59], 0, v[36:37]
	global_load_dword v145, v[166:167], off offset:104
	v_lshl_add_u64 v[166:167], s[58:59], 0, v[36:37]
	global_load_dword v146, v[166:167], off offset:112
	v_lshl_add_u64 v[166:167], s[58:59], 0, v[36:37]
	global_load_dword v147, v[166:167], off offset:120
	s_waitcnt vmcnt(16)
	v_mul_f32_e32 v100, v100, v132
	v_mul_f32_e32 v101, v101, v133
	v_mul_f32_e32 v102, v102, v134
	v_mul_f32_e32 v103, v103, v135
	v_mul_f32_e32 v104, v104, v136
	v_mul_f32_e32 v105, v105, v137
	v_mul_f32_e32 v106, v106, v138
	v_mul_f32_e32 v107, v107, v139
	ds_write_b32 v5, v100
	ds_write_b32 v5, v101 offset:264
	ds_write_b32 v5, v102 offset:528
	ds_write_b32 v5, v103 offset:792
	ds_write_b32 v5, v104 offset:1056
	ds_write_b32 v5, v105 offset:1320
	ds_write_b32 v5, v106 offset:1584
	ds_write_b32 v5, v107 offset:1848
	s_waitcnt vmcnt(0)
	v_mul_f32_e32 v108, v108, v140
	v_mul_f32_e32 v109, v109, v141
	v_mul_f32_e32 v110, v110, v142
	v_mul_f32_e32 v111, v111, v143
	v_mul_f32_e32 v112, v112, v144
	v_mul_f32_e32 v113, v113, v145
	v_mul_f32_e32 v114, v114, v146
	v_mul_f32_e32 v115, v115, v147
	ds_write_b32 v5, v108 offset:2112
	ds_write_b32 v5, v109 offset:2376
	ds_write_b32 v5, v110 offset:2640
	ds_write_b32 v5, v111 offset:2904
	ds_write_b32 v5, v112 offset:3168
	ds_write_b32 v5, v113 offset:3432
	ds_write_b32 v5, v114 offset:3696
	ds_write_b32 v5, v115 offset:3960
	s_mov_b32 s18, 0x48000
	s_mov_b32 s19, 0
	v_lshl_add_u64 v[164:165], v[50:51], 0, s[18:19]
	global_load_dword v100, v[164:165], off
	v_lshl_add_u64 v[164:165], v[48:49], 0, s[18:19]
	global_load_dword v101, v[164:165], off
	v_lshl_add_u64 v[164:165], v[46:47], 0, s[18:19]
	global_load_dword v102, v[164:165], off
	v_lshl_add_u64 v[164:165], v[44:45], 0, s[18:19]
	global_load_dword v103, v[164:165], off
	v_lshl_add_u64 v[164:165], v[42:43], 0, s[18:19]
	global_load_dword v104, v[164:165], off
	v_lshl_add_u64 v[164:165], v[40:41], 0, s[18:19]
	global_load_dword v105, v[164:165], off
	v_lshl_add_u64 v[164:165], v[38:39], 0, s[18:19]
	global_load_dword v106, v[164:165], off
	v_lshl_add_u64 v[164:165], v[34:35], 0, s[18:19]
	global_load_dword v107, v[164:165], off
	v_lshl_add_u64 v[166:167], s[58:59], 0, v[6:7]
	global_load_dword v132, v[166:167], off offset:128
	v_lshl_add_u64 v[166:167], s[58:59], 0, v[36:37]
	global_load_dword v133, v[166:167], off offset:136
	v_lshl_add_u64 v[166:167], s[58:59], 0, v[36:37]
	global_load_dword v134, v[166:167], off offset:144
	v_lshl_add_u64 v[166:167], s[58:59], 0, v[36:37]
	global_load_dword v135, v[166:167], off offset:152
	v_lshl_add_u64 v[166:167], s[58:59], 0, v[36:37]
	global_load_dword v136, v[166:167], off offset:160
	v_lshl_add_u64 v[166:167], s[58:59], 0, v[36:37]
	global_load_dword v137, v[166:167], off offset:168
	v_lshl_add_u64 v[166:167], s[58:59], 0, v[36:37]
	global_load_dword v138, v[166:167], off offset:176
	v_lshl_add_u64 v[166:167], s[58:59], 0, v[36:37]
	global_load_dword v139, v[166:167], off offset:184
	s_mov_b32 s18, 0x6c000
	s_mov_b32 s19, 0
	v_lshl_add_u64 v[164:165], v[50:51], 0, s[18:19]
	global_load_dword v108, v[164:165], off
	v_lshl_add_u64 v[164:165], v[48:49], 0, s[18:19]
	global_load_dword v109, v[164:165], off
	v_lshl_add_u64 v[164:165], v[46:47], 0, s[18:19]
	global_load_dword v110, v[164:165], off
	v_lshl_add_u64 v[164:165], v[44:45], 0, s[18:19]
	global_load_dword v111, v[164:165], off
	v_lshl_add_u64 v[164:165], v[42:43], 0, s[18:19]
	global_load_dword v112, v[164:165], off
	v_lshl_add_u64 v[164:165], v[40:41], 0, s[18:19]
	global_load_dword v113, v[164:165], off
	v_lshl_add_u64 v[164:165], v[38:39], 0, s[18:19]
	global_load_dword v114, v[164:165], off
	v_lshl_add_u64 v[164:165], v[34:35], 0, s[18:19]
	global_load_dword v115, v[164:165], off
	v_lshl_add_u64 v[166:167], s[58:59], 0, v[6:7]
	global_load_dword v140, v[166:167], off offset:192
	v_lshl_add_u64 v[166:167], s[58:59], 0, v[36:37]
	global_load_dword v141, v[166:167], off offset:200
	v_lshl_add_u64 v[166:167], s[58:59], 0, v[36:37]
	global_load_dword v142, v[166:167], off offset:208
	v_lshl_add_u64 v[166:167], s[58:59], 0, v[36:37]
	global_load_dword v143, v[166:167], off offset:216
	v_lshl_add_u64 v[166:167], s[58:59], 0, v[36:37]
	global_load_dword v144, v[166:167], off offset:224
	v_lshl_add_u64 v[166:167], s[58:59], 0, v[36:37]
	global_load_dword v145, v[166:167], off offset:232
	v_lshl_add_u64 v[166:167], s[58:59], 0, v[36:37]
	global_load_dword v146, v[166:167], off offset:240
	v_lshl_add_u64 v[166:167], s[58:59], 0, v[36:37]
	global_load_dword v147, v[166:167], off offset:248
	s_waitcnt vmcnt(16)
	v_mul_f32_e32 v100, v100, v132
	v_mul_f32_e32 v101, v101, v133
	v_mul_f32_e32 v102, v102, v134
	v_mul_f32_e32 v103, v103, v135
	v_mul_f32_e32 v104, v104, v136
	v_mul_f32_e32 v105, v105, v137
	v_mul_f32_e32 v106, v106, v138
	v_mul_f32_e32 v107, v107, v139
	ds_write_b32 v5, v100 offset:4224
	ds_write_b32 v5, v101 offset:4488
	ds_write_b32 v5, v102 offset:4752
	ds_write_b32 v5, v103 offset:5016
	ds_write_b32 v5, v104 offset:5280
	ds_write_b32 v5, v105 offset:5544
	ds_write_b32 v5, v106 offset:5808
	ds_write_b32 v5, v107 offset:6072
	s_waitcnt vmcnt(0)
	v_mul_f32_e32 v108, v108, v140
	v_mul_f32_e32 v109, v109, v141
	v_mul_f32_e32 v110, v110, v142
	v_mul_f32_e32 v111, v111, v143
	v_mul_f32_e32 v112, v112, v144
	v_mul_f32_e32 v113, v113, v145
	v_mul_f32_e32 v114, v114, v146
	v_mul_f32_e32 v115, v115, v147
	ds_write_b32 v5, v108 offset:6336
	ds_write_b32 v5, v109 offset:6600
	ds_write_b32 v5, v110 offset:6864
	ds_write_b32 v5, v111 offset:7128
	ds_write_b32 v5, v112 offset:7392
	ds_write_b32 v5, v113 offset:7656
	ds_write_b32 v5, v114 offset:7920
	ds_write_b32 v5, v115 offset:8184
	v_add_u32_e32 v5, 0x2100, v5
	s_mov_b32 s18, 0x90000
	s_mov_b32 s19, 0
	s_add_u32 s58, s58, 0x100
	s_addc_u32 s59, s59, 0
	s_branch .LBB0_111
